# static s_setprio 1 for waves 4-7 during the dil and GLA mixer phases (incl. mem_attn), reset after; placement preserved
# baseline (speedup 1.0000x reference)
; __global__ void __launch_bounds__(NTHREADS, 2) megak(Params p) {
;     ...
;                 const int sl = st.b0 / SLAB_B, par = sl & 1;
;                 const bf16_t* PJ = PROJ + par * PROJ_SLAB;
;                 DilPrev pv{nullptr, nullptr, nullptr, nullptr, 0};
;                 if (sl > 0) pv = DilPrev{par ? OBUF : OBUF2, LSE + (par ^ 1) * LSE_SLAB, PROJ + (par ^ 1) * PROJ_SLAB, BR, st.b0 - SLAB_B};
;                 dil_attn_phase(lds, PJ, par ? OBUF2 : OBUF, LSE + par * LSE_SLAB, ROPE, SLAB_B * 288, pv, tid, wid, lane);
.LBB0_327:
	s_and_b64 vcc, exec, s[38:39]
	s_cbranch_vccnz .LBB0_437
	s_cmp_lg_u64 s[40:41], 0
	s_cselect_b64 s[50:51], -1, 0
	s_add_u32 s54, s30, s26
	s_addc_u32 s55, s31, s27
	s_mul_i32 s0, s78, 0x2ab
	s_mov_b32 s15, s78
	s_mov_b32 s68, 0x2aaaaaab
	s_movk_i32 s69, 0x81
	v_readlane_b32 s70, v254, 39
	s_mov_b32 s71, 0xffff
	s_mov_b32 s72, 0xff800000
	s_movk_i32 s73, 0x3000
	v_readfirstlane_b32 s100, v32
	s_nop 3
	s_cmpk_lt_u32 s100, 0x100
	s_cbranch_scc1 .Lprio_skip_dil
	s_setprio 1
.Lprio_skip_dil:
	s_nop 0
	s_nop 0
	s_nop 0
	s_nop 0
	s_nop 0
	s_nop 0
	s_nop 0
	s_nop 0
	s_nop 0
	s_nop 0
	s_nop 0
	s_branch .LBB0_331

; __global__ void __launch_bounds__(NTHREADS, 2) megak(Params p) {
;     ...
;                 if (gridDim.x == 256) {
;                     const int grp = blockIdx.x >> 3;
;                     for (int j = 0; j < 2; ++j) mem_attn_item(lds, PJ, DIL_N, DB_QM, DB_GATE, kvl, BR, st.b0, ((blockIdx.x & 7) * 2 + j) + 16 * grp, tid, wid, lane, j == 0);
;                 } else
;                 for (int it = blockIdx.x; it < SLAB_B * 64; it += gridDim.x) mem_attn_item(lds, PJ, DIL_N, DB_QM, DB_GATE, kvl, BR, st.b0, it, tid, wid, lane);
.LBB0_447:
	s_setprio 0
	s_nop 0
	s_nop 0
	s_nop 0
	s_nop 0
	s_nop 0
	s_nop 0
	s_nop 0
	s_nop 0
	s_nop 0
	s_nop 0
	s_nop 0
	s_nop 0
	s_nop 0
	s_nop 0
	s_nop 0
	s_mov_b64 s[22:23], 0

; DI void gla_item(ldsp lds, const Params& p, const bf16_t* proj, bf16_t* obuf, const float* q0k0, int jl, int item, int tid, int wid, int lane) {
;     ...
;     float a00;
;     {
;         const float* qp = q0k0 + b * 768 + h * 96; const float* kp = qp + 384;
;         float t = qp[lane] * kp[lane] + (lane < 32 ? qp[64 + lane] * kp[64 + lane] : 0.f);
;         a00 = wave_sum(t) * 0.10206207261596575f;
;     }
;     f32x4 S[6];
; #pragma unroll
;     for (int i = 0; i < 6; ++i) S[i] = (f32x4){0.f, 0.f, 0.f, 0.f};
;     __syncthreads();
;     const int c0 = tid, c1 = tid + 512;
;     const int row0 = c0 / 12, ch0 = c0 - row0 * 12, row1 = c1 / 12, ch1 = c1 - row1 * 12;
;     const bool has1 = tid < 256;
;     u32x4 qreg0, kreg0, vreg0, qreg1 = (u32x4){0u, 0u, 0u, 0u}, kreg1 = qreg1, vreg1 = qreg1, greg = qreg1;
;     ...
;     GLA_LOAD_CHUNK(0);
.LBB0_482:
	s_or_b64 exec, exec, s[22:23]
	s_lshr_b32 s0, s19, 1
	s_waitcnt lgkmcnt(0)
	v_add_f32_e32 v13, v38, v39
	s_and_b32 s0, s0, 3
	v_mad_i64_i32 v[14:15], s[14:15], s74, v240, v[100:101]
	v_mov_b32_e32 v38, 0x180
	v_mul_f32_e32 v123, 0x3dd105ec, v13
	v_mad_u64_u32 v[124:125], s[14:15], s0, v38, v[14:15]
	v_mad_i64_i32 v[14:15], s[14:15], s74, v240, v[104:105]
	v_mov_b32_e32 v13, 0xc0
	v_mad_u64_u32 v[128:129], s[14:15], s0, v13, v[14:15]
	v_mad_i64_i32 v[14:15], s[14:15], s74, v240, v[106:107]
	v_mad_i64_i32 v[130:131], s[14:15], v36, s94, v[14:15]
	v_mad_i64_i32 v[14:15], s[14:15], s74, v240, v[110:111]
	v_mad_u64_u32 v[132:133], s[14:15], s0, v38, v[14:15]
	v_mad_i64_i32 v[14:15], s[14:15], s74, v240, v[114:115]
	v_mad_u64_u32 v[136:137], s[14:15], s0, v13, v[14:15]
	s_add_u32 s14, s26, s75
	s_addc_u32 s15, s27, 0
	s_mul_i32 s22, s0, 0x180
	s_lshl_b64 s[14:15], s[14:15], 1
	s_add_u32 s14, s14, s22
	s_mul_i32 s34, s74, 0x300000
	s_addc_u32 s15, s15, 0
	s_mul_hi_i32 s23, s74, 0x300000
	s_add_u32 s14, s14, s34
	s_addc_u32 s15, s15, s23
	v_mov_b32_e32 v13, 0x300000
	v_lshl_add_u64 v[138:139], s[14:15], 0, v[116:117]
	v_mad_i64_i32 v[14:15], s[14:15], s74, v13, v[118:119]
	v_mul_lo_u32 v37, v37, s71
	v_mad_u64_u32 v[140:141], s[14:15], s0, v38, v[14:15]
	v_mov_b32_e32 v14, v12
	v_mov_b32_e32 v15, v12
	s_mov_b32 s79, s1
	v_mov_b32_e32 v13, v12
	v_add_u32_e32 v198, v162, v37
	v_mov_b64_e32 v[38:39], v[14:15]
	v_mov_b64_e32 v[50:51], v[14:15]
	v_mov_b64_e32 v[54:55], v[14:15]
	v_mov_b64_e32 v[42:43], v[14:15]
	v_mov_b64_e32 v[46:47], v[14:15]
	v_mov_b64_e32 v[58:59], v[14:15]
	v_lshl_add_u64 v[126:127], v[102:103], 0, s[78:79]
	v_lshl_add_u64 v[134:135], v[112:113], 0, s[78:79]
	v_lshl_add_u64 v[142:143], v[120:121], 0, s[78:79]
	s_mov_b32 s0, 0
	v_mov_b64_e32 v[36:37], v[12:13]
	v_mov_b64_e32 v[48:49], v[12:13]
	v_mov_b64_e32 v[52:53], v[12:13]
	v_mov_b64_e32 v[40:41], v[12:13]
	v_mov_b64_e32 v[44:45], v[12:13]
	v_mov_b64_e32 v[56:57], v[12:13]
	v_readfirstlane_b32 s100, v32
	s_nop 3
	s_cmpk_lt_u32 s100, 0x100
	s_cbranch_scc1 .Lprio_skip_gla
	s_setprio 1

; DI void tok0_gemv(ldsp lds, const float* src, size_t sstride, const float* nw, const float* W, int N, float* Y, int ldy, const float* resid, size_t rstride, int task, int tid, int wid, int lane) {
;     ...
;     {
;         float4 v[4][4];
; #pragma unroll
;         for (int q = 0; q < 4; ++q) { const float* xr = src + (size_t)(wid + 8 * q) * sstride;
; #pragma unroll
;             for (int i = 0; i < 4; ++i) v[q][i] = *(const float4*)(xr + i * 256 + lane * 4); }
; __global__ void __launch_bounds__(NTHREADS, 2) megak(Params p) {
;     ...
;                 if (L == 0) for (int t = blockIdx.x; t < 32; t += gridDim.x)
;                     tok0_gemv(lds, T0BR, 1024, nullptr, p.w_out, 1024, T0X1, 1024, p.x, (size_t)SEQ * 1024, t, tid, wid, lane);
.LBB0_514:
	s_setprio 0
	s_nop 0
	s_nop 0
	s_nop 0
	s_nop 0
	s_nop 0
	s_nop 0
	s_nop 0
	s_nop 0
	s_nop 0
	s_nop 0
	s_nop 0
	s_nop 0
	s_nop 0
	s_nop 0
	s_nop 0
	v_readlane_b32 s14, v252, 14
	v_readlane_b32 s22, v255, 7
	v_readlane_b32 s15, v252, 15
	v_readlane_b32 s23, v255, 8
	s_or_b64 s[14:15], s[22:23], s[14:15]
	s_and_b64 vcc, exec, s[14:15]
	s_cbranch_vccnz .LBB0_652
	v_readlane_b32 s14, v251, 27
	s_waitcnt vmcnt(0)
	v_lshlrev_b32_e32 v8, 4, v238
	v_mov_b32_e32 v9, v12
	v_readlane_b32 s15, v251, 28
	s_ashr_i32 s17, s16, 31
	v_lshrrev_b32_e32 v18, 5, v238
	v_lshl_add_u64 v[0:1], s[14:15], 0, v[8:9]
	s_lshl_b64 s[14:15], s[16:17], 12
	v_lshl_add_u64 v[0:1], v[0:1], 0, s[14:15]
	s_mov_b64 s[14:15], 0x8000
	v_lshl_add_u64 v[2:3], v[0:1], 0, s[14:15]
	s_mov_b64 s[14:15], 0x10000
	v_lshl_add_u64 v[4:5], v[0:1], 0, s[14:15]
	s_lshl_b32 s15, s16, 7
	v_lshl_or_b32 v14, v18, 2, s15
	v_or_b32_e32 v16, 2, v14
	v_ashrrev_i32_e32 v17, 31, v16
	v_lshlrev_b64 v[30:31], 12, v[16:17]
	v_or_b32_e32 v16, 3, v14
	v_ashrrev_i32_e32 v17, 31, v16
	v_lshlrev_b64 v[34:35], 12, v[16:17]
	v_or_b32_e32 v16, 8, v14
	v_ashrrev_i32_e32 v17, 31, v16
	v_lshlrev_b64 v[36:37], 12, v[16:17]
	v_or_b32_e32 v16, 9, v14
	v_ashrrev_i32_e32 v17, 31, v16
	s_waitcnt lgkmcnt(0)
; DI void tok0_gemv(ldsp lds, const float* src, size_t sstride, const float* nw, const float* W, int N, float* Y, int ldy, const float* resid, size_t rstride, int task, int tid, int wid, int lane) {
;     ...
;     const int c0 = task * 32, l31 = lane & 31, kk = lane >> 5, col = c0 + l31; const bool cv = col < N;
;     const int kb = wid * 128;
;     float wv[64];
; #pragma unroll
;     for (int q = 0; q < 16; ++q)
; #pragma unroll
;         for (int e = 0; e < 4; ++e) wv[q * 4 + e] = cv ? W[(size_t)(kb + 8 * q + 4 * kk + e) * N + col] : 0.f;
	v_lshlrev_b64 v[38:39], 12, v[16:17]
	v_or_b32_e32 v16, 10, v14
	v_ashrrev_i32_e32 v17, 31, v16
	v_lshlrev_b64 v[40:41], 12, v[16:17]
	v_or_b32_e32 v16, 11, v14
	v_ashrrev_i32_e32 v17, 31, v16
	v_lshlrev_b64 v[42:43], 12, v[16:17]
	v_or_b32_e32 v16, 16, v14
	v_ashrrev_i32_e32 v17, 31, v16
	v_lshlrev_b64 v[44:45], 12, v[16:17]
	v_or_b32_e32 v16, 17, v14
	v_ashrrev_i32_e32 v17, 31, v16
	v_lshlrev_b64 v[46:47], 12, v[16:17]
	v_or_b32_e32 v16, 18, v14
	v_ashrrev_i32_e32 v17, 31, v16
	v_lshlrev_b64 v[48:49], 12, v[16:17]
	v_or_b32_e32 v16, 19, v14
	v_ashrrev_i32_e32 v17, 31, v16
	v_lshlrev_b64 v[50:51], 12, v[16:17]
	v_or_b32_e32 v16, 24, v14
	v_ashrrev_i32_e32 v17, 31, v16
	v_lshlrev_b64 v[52:53], 12, v[16:17]
	v_or_b32_e32 v16, 25, v14
	v_ashrrev_i32_e32 v17, 31, v16
	v_lshlrev_b64 v[54:55], 12, v[16:17]
	v_or_b32_e32 v16, 26, v14
	v_ashrrev_i32_e32 v17, 31, v16
	v_lshlrev_b64 v[56:57], 12, v[16:17]
	v_or_b32_e32 v16, 27, v14
	v_ashrrev_i32_e32 v17, 31, v16
	v_lshlrev_b64 v[58:59], 12, v[16:17]
	v_or_b32_e32 v16, 32, v14
	v_ashrrev_i32_e32 v17, 31, v16
	v_lshlrev_b64 v[60:61], 12, v[16:17]
	v_or_b32_e32 v16, 33, v14
	v_ashrrev_i32_e32 v17, 31, v16
	v_lshlrev_b64 v[62:63], 12, v[16:17]
	v_or_b32_e32 v16, 34, v14
	v_ashrrev_i32_e32 v17, 31, v16
	v_lshlrev_b64 v[64:65], 12, v[16:17]
	v_or_b32_e32 v16, 35, v14
	v_ashrrev_i32_e32 v17, 31, v16
	v_lshlrev_b64 v[66:67], 12, v[16:17]
	v_or_b32_e32 v16, 40, v14
	v_ashrrev_i32_e32 v17, 31, v16
	v_lshlrev_b64 v[68:69], 12, v[16:17]
	v_or_b32_e32 v16, 41, v14
	v_ashrrev_i32_e32 v17, 31, v16
	v_lshlrev_b64 v[70:71], 12, v[16:17]
	v_or_b32_e32 v16, 42, v14
	v_ashrrev_i32_e32 v17, 31, v16
	v_lshlrev_b64 v[72:73], 12, v[16:17]
	v_or_b32_e32 v16, 43, v14
	v_ashrrev_i32_e32 v17, 31, v16
	v_lshlrev_b64 v[74:75], 12, v[16:17]
	v_or_b32_e32 v16, 48, v14
	v_ashrrev_i32_e32 v17, 31, v16
	v_lshlrev_b64 v[76:77], 12, v[16:17]
	v_or_b32_e32 v16, 49, v14
	v_ashrrev_i32_e32 v17, 31, v16
	v_lshlrev_b64 v[78:79], 12, v[16:17]
	v_or_b32_e32 v16, 50, v14
	v_ashrrev_i32_e32 v17, 31, v16
	v_lshlrev_b64 v[80:81], 12, v[16:17]
	v_or_b32_e32 v16, 51, v14
	v_ashrrev_i32_e32 v17, 31, v16
	v_lshlrev_b64 v[82:83], 12, v[16:17]
	v_or_b32_e32 v16, 56, v14
	v_ashrrev_i32_e32 v17, 31, v16
	v_lshlrev_b64 v[84:85], 12, v[16:17]
	v_or_b32_e32 v16, 57, v14
	v_ashrrev_i32_e32 v17, 31, v16
	v_lshlrev_b64 v[86:87], 12, v[16:17]
	v_or_b32_e32 v16, 58, v14
	v_ashrrev_i32_e32 v17, 31, v16
	v_lshlrev_b64 v[88:89], 12, v[16:17]
	v_or_b32_e32 v16, 59, v14
	v_ashrrev_i32_e32 v17, 31, v16
	v_lshlrev_b64 v[90:91], 12, v[16:17]
	v_or_b32_e32 v16, 64, v14
	v_ashrrev_i32_e32 v17, 31, v16
	v_lshlrev_b64 v[92:93], 12, v[16:17]
	v_or_b32_e32 v16, 0x41, v14
	v_ashrrev_i32_e32 v17, 31, v16
	v_lshlrev_b64 v[94:95], 12, v[16:17]
	v_or_b32_e32 v16, 0x42, v14
	v_ashrrev_i32_e32 v17, 31, v16
	v_lshlrev_b64 v[96:97], 12, v[16:17]
	v_or_b32_e32 v16, 0x43, v14
	v_ashrrev_i32_e32 v17, 31, v16
	v_lshlrev_b64 v[98:99], 12, v[16:17]
	v_or_b32_e32 v16, 0x48, v14
	v_ashrrev_i32_e32 v17, 31, v16
	v_lshlrev_b64 v[100:101], 12, v[16:17]
	v_or_b32_e32 v16, 0x49, v14
	v_ashrrev_i32_e32 v17, 31, v16
	v_lshlrev_b64 v[102:103], 12, v[16:17]
	v_or_b32_e32 v16, 0x4a, v14
	v_ashrrev_i32_e32 v17, 31, v16
	v_lshlrev_b64 v[104:105], 12, v[16:17]
	v_or_b32_e32 v16, 0x4b, v14
	v_ashrrev_i32_e32 v17, 31, v16
	v_lshlrev_b64 v[106:107], 12, v[16:17]
	v_or_b32_e32 v16, 0x50, v14
	v_ashrrev_i32_e32 v17, 31, v16
	v_lshlrev_b64 v[108:109], 12, v[16:17]
	v_or_b32_e32 v16, 0x51, v14
	v_ashrrev_i32_e32 v17, 31, v16
	v_lshlrev_b64 v[110:111], 12, v[16:17]
	v_or_b32_e32 v16, 0x52, v14
	v_ashrrev_i32_e32 v17, 31, v16
	v_lshlrev_b64 v[112:113], 12, v[16:17]
	v_or_b32_e32 v16, 0x53, v14
	v_ashrrev_i32_e32 v17, 31, v16
	v_lshlrev_b64 v[114:115], 12, v[16:17]
	v_or_b32_e32 v16, 0x58, v14
	v_ashrrev_i32_e32 v17, 31, v16
	v_lshlrev_b64 v[116:117], 12, v[16:17]
	v_or_b32_e32 v16, 0x59, v14
	v_ashrrev_i32_e32 v17, 31, v16
	v_lshlrev_b64 v[118:119], 12, v[16:17]
	v_or_b32_e32 v16, 0x5a, v14
	v_ashrrev_i32_e32 v17, 31, v16
	v_lshlrev_b64 v[120:121], 12, v[16:17]
	v_or_b32_e32 v16, 0x5b, v14
	v_ashrrev_i32_e32 v17, 31, v16
	v_lshlrev_b64 v[122:123], 12, v[16:17]
	v_or_b32_e32 v16, 0x60, v14
	v_ashrrev_i32_e32 v17, 31, v16
	v_lshlrev_b64 v[124:125], 12, v[16:17]
	v_or_b32_e32 v16, 0x61, v14
	v_ashrrev_i32_e32 v17, 31, v16
	v_lshlrev_b64 v[126:127], 12, v[16:17]
	v_or_b32_e32 v16, 0x62, v14
	v_ashrrev_i32_e32 v17, 31, v16
	v_lshlrev_b64 v[128:129], 12, v[16:17]
	v_or_b32_e32 v16, 0x63, v14
	v_ashrrev_i32_e32 v17, 31, v16
	v_lshlrev_b64 v[130:131], 12, v[16:17]
	v_or_b32_e32 v16, 0x68, v14
	v_ashrrev_i32_e32 v17, 31, v16
	v_lshlrev_b64 v[132:133], 12, v[16:17]
	v_or_b32_e32 v16, 0x69, v14
	v_ashrrev_i32_e32 v17, 31, v16
	v_lshlrev_b64 v[134:135], 12, v[16:17]
	v_or_b32_e32 v16, 0x6a, v14
	v_ashrrev_i32_e32 v17, 31, v16
	v_lshlrev_b64 v[136:137], 12, v[16:17]
	v_or_b32_e32 v16, 0x6b, v14
	v_ashrrev_i32_e32 v17, 31, v16
	v_lshlrev_b64 v[138:139], 12, v[16:17]
	v_or_b32_e32 v16, 0x70, v14
	v_ashrrev_i32_e32 v17, 31, v16
	v_lshlrev_b64 v[140:141], 12, v[16:17]
	v_or_b32_e32 v16, 0x71, v14
	v_ashrrev_i32_e32 v17, 31, v16
	v_lshlrev_b64 v[142:143], 12, v[16:17]
	v_or_b32_e32 v16, 0x72, v14
	v_ashrrev_i32_e32 v17, 31, v16
	v_lshlrev_b64 v[144:145], 12, v[16:17]
	v_or_b32_e32 v16, 0x73, v14
	v_ashrrev_i32_e32 v17, 31, v16
	v_lshlrev_b64 v[146:147], 12, v[16:17]
	v_or_b32_e32 v16, 0x78, v14
	v_ashrrev_i32_e32 v17, 31, v16
	v_lshlrev_b64 v[148:149], 12, v[16:17]
	v_or_b32_e32 v16, 0x79, v14
	v_ashrrev_i32_e32 v15, 31, v14
	v_ashrrev_i32_e32 v17, 31, v16
	v_add_u32_e32 v13, 0, v8
	v_lshlrev_b64 v[8:9], 12, v[14:15]
	v_or_b32_e32 v10, 1, v14
	v_lshlrev_b64 v[150:151], 12, v[16:17]
	v_or_b32_e32 v16, 0x7a, v14
	v_or_b32_e32 v14, 0x7b, v14
	v_and_b32_e32 v33, 31, v32
	v_ashrrev_i32_e32 v15, 31, v14
	s_movk_i32 s15, 0x1010
	v_ashrrev_i32_e32 v17, 31, v16
	v_lshlrev_b64 v[162:163], 12, v[14:15]
	v_mad_u32_u24 v14, v33, s15, 0
	s_lshl_b32 s15, s16, 12
	v_lshlrev_b64 v[152:153], 12, v[16:17]
	v_lshlrev_b32_e32 v16, 4, v18
	s_add_i32 s15, s15, 0
	v_lshlrev_b32_e32 v17, 9, v18
	v_lshlrev_b32_e32 v18, 2, v33
	v_add3_u32 v155, s15, v17, v18
	s_movk_i32 s15, 0x400
	s_mul_i32 s0, s16, 0x1010
	v_ashrrev_i32_e32 v11, 31, v10
	v_lshl_add_u32 v15, s16, 9, v14
	v_cmp_gt_i32_e64 s[38:39], s15, v32
	s_movk_i32 s15, 0xeff4
	v_lshl_add_u64 v[6:7], v[0:1], 0, s[28:29]
	s_add_i32 s14, s0, 0x10100
	v_lshlrev_b64 v[10:11], 12, v[10:11]
	v_mad_i32_i24 v156, v33, s15, v14
	v_add_u32_e32 v166, v15, v16
	s_mov_b32 s15, s78
	s_branch .LBB0_517
